# S5 helper scan: two steps' outputs per ds_write2_b32 (8 LDS writes per chunk instead of 16)
# speedup vs baseline: 1.0164x; 1.0164x over previous
.LBB0_398:
	s_or_b64 exec, exec, s[38:39]
	v_lshl_or_b32 v2, s8, 10, v142
	v_mov_b32_e32 v3, v0
	v_lshl_add_u64 v[2:3], v[68:69], 0, v[2:3]
	global_load_ushort v212, v[2:3], off
	global_load_ushort v213, v[2:3], off offset:1024
	global_load_ushort v214, v[2:3], off offset:2048
	global_load_ushort v215, v[2:3], off offset:3072
	v_add_u32_e32 v91, v143, v102
	ds_read_b128 v[92:95], v91 offset:12544
	ds_read_b128 v[164:167], v91 offset:13056
	ds_read_b128 v[216:219], v91 offset:13568
	ds_read_b128 v[220:223], v146 offset:12544
	ds_read_b128 v[224:227], v91 offset:14592
	ds_read_b128 v[228:231], v91 offset:15104
	ds_read_b128 v[244:247], v91 offset:15616
	ds_read_b128 v[248:251], v147 offset:12544
	v_add_u32_e32 v96, 0xf000, v138
	v_add_u32_e32 v97, 0xf400, v138
	v_add_u32_e32 v159, 0xf800, v138
	s_andn2_b64 vcc, exec, s[50:51]
	s_waitcnt lgkmcnt(7)
	v_mfma_f32_16x16x32_bf16 v[92:95], v[12:15], v[92:95], 0
	s_waitcnt lgkmcnt(6)
	v_mfma_f32_16x16x32_bf16 v[164:167], v[12:15], v[164:167], 0
	s_waitcnt lgkmcnt(5)
	v_mfma_f32_16x16x32_bf16 v[216:219], v[12:15], v[216:219], 0
	s_waitcnt lgkmcnt(4)
	v_mfma_f32_16x16x32_bf16 v[220:223], v[12:15], v[220:223], 0
	s_waitcnt lgkmcnt(3)
	v_mfma_f32_16x16x32_bf16 v[224:227], v[12:15], v[224:227], 0
	s_waitcnt lgkmcnt(2)
	v_mfma_f32_16x16x32_bf16 v[228:231], v[12:15], v[228:231], 0
	s_waitcnt lgkmcnt(1)
	v_mfma_f32_16x16x32_bf16 v[244:247], v[12:15], v[244:247], 0
	s_waitcnt lgkmcnt(0)
	v_mfma_f32_16x16x32_bf16 v[248:251], v[12:15], v[248:251], 0
	ds_write2_b32 v96, v92, v164 offset0:192 offset1:208
	ds_write2_b32 v97, v93, v165 offset0:64 offset1:80
	ds_write2_b32 v97, v94, v166 offset0:192 offset1:208
	ds_write2_b32 v159, v95, v167 offset0:64 offset1:80
	ds_write2_b32 v96, v216, v220 offset0:224 offset1:240
	ds_write2_b32 v97, v217, v221 offset0:96 offset1:112
	ds_write2_b32 v97, v218, v222 offset0:224 offset1:240
	ds_write2_b32 v159, v219, v223 offset0:96 offset1:112
	ds_write2_b32 v97, v224, v228 offset1:16
	ds_write2_b32 v97, v225, v229 offset0:128 offset1:144
	ds_write2_b32 v159, v226, v230 offset1:16
	ds_write2_b32 v159, v227, v231 offset0:128 offset1:144
	ds_write2_b32 v97, v244, v248 offset0:32 offset1:48
	ds_write2_b32 v97, v245, v249 offset0:160 offset1:176
	ds_write2_b32 v159, v246, v250 offset0:32 offset1:48
	ds_write2_b32 v159, v247, v251 offset0:160 offset1:176
	s_waitcnt lgkmcnt(0)
	v_lshl_add_u32 v91, v98, 1, v141
	v_add_u32_e32 v96, 0x2000, v91
	v_add_u32_e32 v97, 0x2440, v91
	v_add_u32_e32 v159, 0x2880, v91
	v_add_u32_e32 v91, 0x2cc0, v91
	ds_read2st64_b32 v[216:217], v140 offset1:1
	ds_read2st64_b32 v[218:219], v140 offset0:2 offset1:3
	ds_read2st64_b32 v[220:221], v140 offset0:4 offset1:5
	ds_read2st64_b32 v[222:223], v140 offset0:6 offset1:7
	ds_read2st64_b32 v[224:225], v140 offset0:8 offset1:9
	ds_read2st64_b32 v[226:227], v140 offset0:10 offset1:11
	ds_read2st64_b32 v[228:229], v140 offset0:12 offset1:13
	ds_read2st64_b32 v[230:231], v140 offset0:14 offset1:15
	ds_read2st64_b32 v[244:245], v140 offset0:16 offset1:17
	ds_read2st64_b32 v[246:247], v140 offset0:18 offset1:19
	ds_read2st64_b32 v[248:249], v140 offset0:20 offset1:21
	ds_read2st64_b32 v[250:251], v140 offset0:22 offset1:23
	ds_read2st64_b32 v[92:93], v140 offset0:24 offset1:25
	ds_read2st64_b32 v[94:95], v140 offset0:26 offset1:27
	ds_read2st64_b32 v[164:165], v140 offset0:28 offset1:29
	ds_read2st64_b32 v[166:167], v140 offset0:30 offset1:31
	s_waitcnt lgkmcnt(15)
	v_pk_fma_f32 v[14:15], v[64:65], v[60:61], v[216:217] op_sel:[0,1,0] op_sel_hi:[0,0,1] neg_lo:[1,0,0]
	v_pk_fma_f32 v[60:61], v[56:57], v[60:61], v[14:15] op_sel_hi:[0,1,1]
	v_cvt_pk_bf16_f32 v12, v60, v61
	s_waitcnt lgkmcnt(14)
	v_pk_fma_f32 v[14:15], v[64:65], v[60:61], v[218:219] op_sel:[0,1,0] op_sel_hi:[0,0,1] neg_lo:[1,0,0]
	v_pk_fma_f32 v[60:61], v[56:57], v[60:61], v[14:15] op_sel_hi:[0,1,1]
	v_cvt_pk_bf16_f32 v13, v60, v61
	ds_write2_b32 v96, v12, v13 offset0:0 offset1:68
	s_waitcnt lgkmcnt(14)
	v_pk_fma_f32 v[14:15], v[64:65], v[60:61], v[220:221] op_sel:[0,1,0] op_sel_hi:[0,0,1] neg_lo:[1,0,0]
	v_pk_fma_f32 v[60:61], v[56:57], v[60:61], v[14:15] op_sel_hi:[0,1,1]
	v_cvt_pk_bf16_f32 v12, v60, v61
	s_waitcnt lgkmcnt(13)
	v_pk_fma_f32 v[14:15], v[64:65], v[60:61], v[222:223] op_sel:[0,1,0] op_sel_hi:[0,0,1] neg_lo:[1,0,0]
	v_pk_fma_f32 v[60:61], v[56:57], v[60:61], v[14:15] op_sel_hi:[0,1,1]
	v_cvt_pk_bf16_f32 v13, v60, v61
	ds_write2_b32 v96, v12, v13 offset0:136 offset1:204
	s_waitcnt lgkmcnt(13)
	v_pk_fma_f32 v[14:15], v[64:65], v[60:61], v[224:225] op_sel:[0,1,0] op_sel_hi:[0,0,1] neg_lo:[1,0,0]
	v_pk_fma_f32 v[60:61], v[56:57], v[60:61], v[14:15] op_sel_hi:[0,1,1]
	v_cvt_pk_bf16_f32 v12, v60, v61
	s_waitcnt lgkmcnt(12)
	v_pk_fma_f32 v[14:15], v[64:65], v[60:61], v[226:227] op_sel:[0,1,0] op_sel_hi:[0,0,1] neg_lo:[1,0,0]
	v_pk_fma_f32 v[60:61], v[56:57], v[60:61], v[14:15] op_sel_hi:[0,1,1]
	v_cvt_pk_bf16_f32 v13, v60, v61
	ds_write2_b32 v97, v12, v13 offset0:0 offset1:68
	s_waitcnt lgkmcnt(12)
	v_pk_fma_f32 v[14:15], v[64:65], v[60:61], v[228:229] op_sel:[0,1,0] op_sel_hi:[0,0,1] neg_lo:[1,0,0]
	v_pk_fma_f32 v[60:61], v[56:57], v[60:61], v[14:15] op_sel_hi:[0,1,1]
	v_cvt_pk_bf16_f32 v12, v60, v61
	s_waitcnt lgkmcnt(11)
	v_pk_fma_f32 v[14:15], v[64:65], v[60:61], v[230:231] op_sel:[0,1,0] op_sel_hi:[0,0,1] neg_lo:[1,0,0]
	v_pk_fma_f32 v[60:61], v[56:57], v[60:61], v[14:15] op_sel_hi:[0,1,1]
	v_cvt_pk_bf16_f32 v13, v60, v61
	ds_write2_b32 v97, v12, v13 offset0:136 offset1:204
	s_waitcnt lgkmcnt(11)
	v_pk_fma_f32 v[14:15], v[64:65], v[60:61], v[244:245] op_sel:[0,1,0] op_sel_hi:[0,0,1] neg_lo:[1,0,0]
	v_pk_fma_f32 v[60:61], v[56:57], v[60:61], v[14:15] op_sel_hi:[0,1,1]
	v_cvt_pk_bf16_f32 v12, v60, v61
	s_waitcnt lgkmcnt(10)
	v_pk_fma_f32 v[14:15], v[64:65], v[60:61], v[246:247] op_sel:[0,1,0] op_sel_hi:[0,0,1] neg_lo:[1,0,0]
	v_pk_fma_f32 v[60:61], v[56:57], v[60:61], v[14:15] op_sel_hi:[0,1,1]
	v_cvt_pk_bf16_f32 v13, v60, v61
	ds_write2_b32 v159, v12, v13 offset0:0 offset1:68
	s_waitcnt lgkmcnt(10)
	v_pk_fma_f32 v[14:15], v[64:65], v[60:61], v[248:249] op_sel:[0,1,0] op_sel_hi:[0,0,1] neg_lo:[1,0,0]
	v_pk_fma_f32 v[60:61], v[56:57], v[60:61], v[14:15] op_sel_hi:[0,1,1]
	v_cvt_pk_bf16_f32 v12, v60, v61
	s_waitcnt lgkmcnt(9)
	v_pk_fma_f32 v[14:15], v[64:65], v[60:61], v[250:251] op_sel:[0,1,0] op_sel_hi:[0,0,1] neg_lo:[1,0,0]
	v_pk_fma_f32 v[60:61], v[56:57], v[60:61], v[14:15] op_sel_hi:[0,1,1]
	v_cvt_pk_bf16_f32 v13, v60, v61
	ds_write2_b32 v159, v12, v13 offset0:136 offset1:204
	s_waitcnt lgkmcnt(9)
	v_pk_fma_f32 v[14:15], v[64:65], v[60:61], v[92:93] op_sel:[0,1,0] op_sel_hi:[0,0,1] neg_lo:[1,0,0]
	v_pk_fma_f32 v[60:61], v[56:57], v[60:61], v[14:15] op_sel_hi:[0,1,1]
	v_cvt_pk_bf16_f32 v12, v60, v61
	s_waitcnt lgkmcnt(8)
	v_pk_fma_f32 v[14:15], v[64:65], v[60:61], v[94:95] op_sel:[0,1,0] op_sel_hi:[0,0,1] neg_lo:[1,0,0]
	v_pk_fma_f32 v[60:61], v[56:57], v[60:61], v[14:15] op_sel_hi:[0,1,1]
	v_cvt_pk_bf16_f32 v13, v60, v61
	ds_write2_b32 v91, v12, v13 offset0:0 offset1:68
	s_waitcnt lgkmcnt(8)
	v_pk_fma_f32 v[14:15], v[64:65], v[60:61], v[164:165] op_sel:[0,1,0] op_sel_hi:[0,0,1] neg_lo:[1,0,0]
	v_pk_fma_f32 v[60:61], v[56:57], v[60:61], v[14:15] op_sel_hi:[0,1,1]
	v_cvt_pk_bf16_f32 v12, v60, v61
	s_waitcnt lgkmcnt(7)
	v_pk_fma_f32 v[14:15], v[64:65], v[60:61], v[166:167] op_sel:[0,1,0] op_sel_hi:[0,0,1] neg_lo:[1,0,0]
	v_pk_fma_f32 v[60:61], v[56:57], v[60:61], v[14:15] op_sel_hi:[0,1,1]
	v_cvt_pk_bf16_f32 v13, v60, v61
	ds_write2_b32 v91, v12, v13 offset0:136 offset1:204
	s_waitcnt lgkmcnt(0)
	ds_read_b128 v[12:15], v144 offset:8192
	ds_read_b128 v[92:95], v145 offset:16640
	ds_read_b128 v[216:219], v144 offset:8256
	ds_read_b128 v[220:223], v145 offset:16704
	ds_read_b128 v[224:227], v144 offset:8320
	ds_read_b128 v[228:231], v145 offset:16768
	ds_read_b128 v[244:247], v144 offset:8384
	ds_read_b128 v[248:251], v145 offset:16832
	s_waitcnt lgkmcnt(6)
	v_mfma_f32_16x16x32_bf16 v[12:15], v[12:15], v[92:95], 0
	s_waitcnt lgkmcnt(4)
	v_mfma_f32_16x16x32_bf16 v[12:15], v[216:219], v[220:223], v[12:15]
	s_waitcnt lgkmcnt(2)
	v_mfma_f32_16x16x32_bf16 v[12:15], v[224:227], v[228:231], v[12:15]
	s_waitcnt lgkmcnt(0)
	v_mfma_f32_16x16x32_bf16 v[12:15], v[244:247], v[248:251], v[12:15]
	s_nop 7
	s_waitcnt vmcnt(0)
	v_lshlrev_b32_e32 v88, 16, v212
	v_lshlrev_b32_e32 v89, 16, v213
	v_lshlrev_b32_e32 v90, 16, v214
	v_lshlrev_b32_e32 v91, 16, v215
	v_pk_fma_f32 v[12:13], v[148:149], v[88:89], v[12:13] op_sel_hi:[0,1,1]
	v_pk_fma_f32 v[14:15], v[148:149], v[90:91], v[14:15] op_sel_hi:[0,1,1]
	v_mov_b32_e32 v88, 0x3dd2d3e8
	v_mov_b32_e32 v90, 0x40135761
	v_pk_mul_f32 v[92:93], v[12:13], v[12:13]
	v_pk_mul_f32 v[94:95], v[14:15], v[14:15]
	v_pk_fma_f32 v[92:93], v[92:93], v[88:89], v[90:91] op_sel_hi:[1,0,0]
	v_pk_fma_f32 v[94:95], v[94:95], v[88:89], v[90:91] op_sel_hi:[1,0,0]
	v_pk_mul_f32 v[92:93], v[92:93], v[12:13]
	v_pk_mul_f32 v[94:95], v[94:95], v[14:15]
	v_mov_b32_e32 v88, 1.0
	v_exp_f32_e32 v92, v92
	v_exp_f32_e32 v93, v93
	v_exp_f32_e32 v94, v94
	v_exp_f32_e32 v95, v95
	s_nop 0
	v_pk_add_f32 v[92:93], v[92:93], v[88:89] op_sel_hi:[1,0]
	v_pk_add_f32 v[94:95], v[94:95], v[88:89] op_sel_hi:[1,0]
	v_rcp_f32_e32 v92, v92
	v_rcp_f32_e32 v93, v93
	v_rcp_f32_e32 v94, v94
	v_rcp_f32_e32 v95, v95
	s_nop 0
	v_pk_fma_f32 v[12:13], v[12:13], v[92:93], v[12:13] neg_lo:[1,0,0] neg_hi:[1,0,0]
	v_pk_fma_f32 v[14:15], v[14:15], v[94:95], v[14:15] neg_lo:[1,0,0] neg_hi:[1,0,0]
	v_cvt_pk_bf16_f32 v12, v12, v13
	v_cvt_pk_bf16_f32 v14, v14, v15
	global_store_short v[2:3], v12, off
	global_store_short_d16_hi v[2:3], v12, off offset:1024
	global_store_short v[2:3], v14, off offset:2048
	global_store_short_d16_hi v[2:3], v14, off offset:3072
	s_waitcnt lgkmcnt(0)
	v_lshlrev_b32_e32 v1, 2, v128
	s_cbranch_vccnz .LBB0_408
	s_waitcnt vmcnt(4)
	v_lshlrev_b32_e32 v16, 16, v176
	v_lshlrev_b32_e32 v30, 16, v177
	v_lshlrev_b32_e32 v32, 16, v178
	v_lshlrev_b32_e32 v36, 16, v179
	v_lshlrev_b32_e32 v17, 16, v180
	v_lshlrev_b32_e32 v26, 16, v181
	v_lshlrev_b32_e32 v27, 16, v182
	v_lshlrev_b32_e32 v28, 16, v183
	v_lshlrev_b32_e32 v29, 16, v184
	v_lshlrev_b32_e32 v31, 16, v185
	v_lshlrev_b32_e32 v33, 16, v186
	v_lshlrev_b32_e32 v37, 16, v187
	v_lshlrev_b32_e32 v34, 16, v188
	v_lshlrev_b32_e32 v35, 16, v189
	v_lshlrev_b32_e32 v38, 16, v190
	v_lshlrev_b32_e32 v39, 16, v195
	v_lshlrev_b32_e32 v40, 16, v197
	v_lshlrev_b32_e32 v43, 16, v198
	v_lshlrev_b32_e32 v42, 16, v199
	v_lshlrev_b32_e32 v45, 16, v200
	v_lshlrev_b32_e32 v44, 16, v201
	v_lshlrev_b32_e32 v46, 16, v203
	v_lshlrev_b32_e32 v49, 16, v204
	v_lshlrev_b32_e32 v48, 16, v205
	v_lshlrev_b32_e32 v41, 16, v196
	v_lshlrev_b32_e32 v47, 16, v202
	v_lshlrev_b32_e32 v51, 16, v206
	v_lshlrev_b32_e32 v50, 16, v207
	v_lshlrev_b32_e32 v53, 16, v191
	v_lshlrev_b32_e32 v52, 16, v193
	v_lshlrev_b32_e32 v55, 16, v192
	v_lshlrev_b32_e32 v54, 16, v194
	v_add_f32_e32 v88, v155, v35
	v_mul_f32_e32 v88, 0xbfb8aa3b, v88
	v_exp_f32_e32 v88, v88
	v_pk_add_f32 v[12:13], v[32:33], v[26:27] neg_lo:[0,1] neg_hi:[0,1]
	v_pk_add_f32 v[2:3], v[30:31], v[16:17] neg_lo:[0,1] neg_hi:[0,1]
	v_fma_f32 v13, v150, v13, v27
	v_add_f32_e32 v88, 1.0, v88
	v_rcp_f32_e32 v88, v88
	v_mul_f32_e32 v92, v157, v13
	v_fma_f32 v3, v149, v3, v17
	s_bitcmp1_b32 s3, 0
	v_mul_f32_e32 v89, 0xbf6002b1, v88
	v_cmp_gt_f32_e32 vcc, s85, v89
	s_cselect_b32 s8, 0x5000, 0
	v_mov_b32_e32 v94, v0
	v_cndmask_b32_e32 v89, 0, v239, vcc
	v_fmac_f32_e32 v89, 0xbf6002b1, v88
	v_exp_f32_e32 v88, v89
	v_cndmask_b32_e32 v89, 0, v236, vcc
	s_add_i32 s9, s8, 0
	s_mul_i32 s8, s3, 0xab
	v_ldexp_f32 v90, v88, v89
	v_add_f32_e32 v88, v154, v39
	v_mul_f32_e32 v88, 0xbfb8aa3b, v88
	v_exp_f32_e32 v88, v88
	v_mov_b32_e32 v89, v0
	s_bfe_u32 s8, s8, 0x70009
	s_mul_i32 s8, s8, 3
	v_add_f32_e32 v88, 1.0, v88
	v_rcp_f32_e32 v91, v88
	v_mul_f32_e32 v88, v92, v92
	s_sub_i32 s8, s3, s8
	s_and_b32 s8, s8, 0xff
	v_mov_b32_dpp v89, v88 quad_perm:[1,0,3,2] row_mask:0xf bank_mask:0xf
	v_fmac_f32_e32 v89, v92, v92
	s_mulk_i32 s8, 0x1100
	s_add_i32 s8, s8, 0
	v_add_f32_dpp v88, v89, v89 quad_perm:[2,3,0,1] row_mask:0xf bank_mask:0xf bound_ctrl:1
	v_pk_add_f32 v[14:15], v[36:37], v[28:29] neg_lo:[0,1] neg_hi:[0,1]
	s_nop 0
	v_add_f32_dpp v88, v88, v88 row_half_mirror row_mask:0xf bank_mask:0xf bound_ctrl:1
	v_fma_f32 v15, v151, v15, v29
	s_nop 0
	v_add_f32_dpp v88, v88, v88 row_mirror row_mask:0xf bank_mask:0xf bound_ctrl:1
	s_nop 0
	s_nop 1
	v_add_f32_dpp v88, v88, v88 row_bcast:15 row_mask:0xa bank_mask:0xf
	s_nop 1
	v_add_f32_dpp v88, v88, v88 row_bcast:31 row_mask:0xc bank_mask:0xf
	s_nop 0
	v_readlane_b32 s26, v88, 63
	s_nop 1
	v_mov_b32_e32 v88, s26
	v_add_f32_e32 v88, 0x2b8cbccc, v88
	v_cmp_gt_f32_e32 vcc, s82, v88
	v_mul_f32_e32 v89, 0x4b800000, v88
	s_nop 0
	v_cndmask_b32_e32 v88, v88, v89, vcc
	v_rsq_f32_e32 v88, v88
	s_nop 0
	v_mul_f32_e32 v89, 0x45800000, v88
	v_cndmask_b32_e32 v88, v88, v89, vcc
	v_add_f32_e32 v89, -1.0, v91
	v_fma_f32 v89, v158, v89, 1.0
	v_mul_f32_e32 v13, v89, v13
	v_mul_f32_e32 v89, v13, v3
	v_mul_f32_e32 v93, v156, v89
	v_mul_f32_e64 v88, v92, -v88
	s_nop 0
	v_mov_b32_dpp v94, v93 quad_perm:[1,0,3,2] row_mask:0xf bank_mask:0xf
	v_fmac_f32_e32 v94, v156, v89
	s_nop 1
	v_add_f32_dpp v89, v94, v94 quad_perm:[2,3,0,1] row_mask:0xf bank_mask:0xf bound_ctrl:1
	s_nop 1
	v_add_f32_dpp v89, v89, v89 row_half_mirror row_mask:0xf bank_mask:0xf bound_ctrl:1
	s_nop 1
	v_add_f32_dpp v89, v89, v89 row_mirror row_mask:0xf bank_mask:0xf bound_ctrl:1
	s_nop 0
	s_nop 1
	v_add_f32_dpp v89, v89, v89 row_bcast:15 row_mask:0xa bank_mask:0xf
	s_nop 1
	v_add_f32_dpp v89, v89, v89 row_bcast:31 row_mask:0xc bank_mask:0xf
	s_nop 0
	v_readlane_b32 s38, v89, 63
	v_add_u32_e32 v89, s9, v1
	ds_write2st64_b32 v89, v90, v88 offset1:16
	v_mul_f32_e64 v88, v91, -v88
	ds_write2st64_b32 v89, v88, v13 offset0:32 offset1:48
	ds_write_b32 v89, v3 offset:16384
	v_add_u32_e32 v3, s8, v1
	ds_write_b32 v3, v15 offset:40960
	s_and_saveexec_b64 s[50:51], s[44:45]
	s_cbranch_execz .LBB0_401
	s_lshl_b32 s24, s96, 2
	s_add_i32 s24, s8, s24
	v_mov_b32_e32 v13, s24
	v_mov_b32_e32 v3, s38
	ds_write_b32 v13, v3 offset:45056
